# row pass: both prefetch streams (odd and even rows) issue their fp16 residual and F loads one row-process earlier; first odd-row loads issued before the loop
# baseline (speedup 1.0000x reference)
; __device__ __forceinline__ void row_load(const RowArgs& R, int m, int lane, RowRaw& q) {
;     const size_t off = (size_t)m * DM + 8 * lane;
;     if (R.hin32) {
; #pragma unroll
;         for (int j = 0; j < 2; ++j) { q.v32[j][0] = __builtin_nontemporal_load((const f32x4*)(R.hin32 + off + 512 * j)); q.v32[j][1] = __builtin_nontemporal_load((const f32x4*)(R.hin32 + off + 512 * j + 4)); }
;     } else {
; #pragma unroll
;         for (int j = 0; j < 2; ++j) q.v16[j] = __builtin_nontemporal_load((const u32x4*)(R.hin16 + off + 512 * j));
;     }
;     if (R.F) {
; #pragma unroll
;         for (int j = 0; j < 2; ++j) q.f[j] = __builtin_nontemporal_load((const u32x4*)(R.F + off + 512 * j));
;     }
; __device__ __forceinline__ void row_pass(const RowArgs& R, int gw, int NGW, int lane, LAS unsigned char* lds, int tid) {
;     ...
;     RowRaw qa, qb;
;     if (gw < M) row_load(R, gw, lane, qa);
;     for (int m = gw; m < M; m += 2 * NGW) {
;         const int m1 = m + NGW, m2 = m + 2 * NGW;
;         if (m1 < M) row_load(R, m1, lane, qb);
.LBB0_247:
	s_mov_b32 s59, 0xf800000
	s_andn2_b64 vcc, exec, s[10:11]
	s_cbranch_vccnz .LBB0_309
	s_waitcnt lgkmcnt(0)
	s_lshl_b32 s30, s3, 3
	s_cmp_lg_u64 s[78:79], 0
	s_cselect_b64 s[34:35], -1, 0
	s_cmp_lg_u64 s[96:97], 0
	s_cselect_b64 s[36:37], -1, 0
	s_cmp_lg_u64 s[80:81], 0
	v_lshlrev_b32_e32 v0, 4, v80
	s_cselect_b64 s[38:39], -1, 0
	s_cmp_lg_u64 s[14:15], 0
	v_mov_b32_e32 v143, v1
	v_add_u32_e32 v30, 0, v0
	v_cmp_eq_u32_e64 s[10:11], 0, v80
	v_lshl_add_u64 v[26:27], s[14:15], 0, v[0:1]
	s_cselect_b64 s[42:43], -1, 0
	v_lshl_add_u64 v[146:147], s[12:13], 0, v[142:143]
	s_mov_b32 s77, s76
	s_lshl_b32 s89, s3, 4
	s_and_b64 vcc, exec, s[34:35]
	s_cbranch_vccnz .Lrp_pre_done
	s_add_i32 s98, s68, s30
	s_cmp_gt_i32 s98, 0xffff
	s_cbranch_scc1 .Lrp_pre_done
	s_ashr_i32 s99, s98, 31
	s_lshl_b64 s[98:99], s[98:99], 10
	v_mov_b32_e32 v39, s99
	v_or_b32_e32 v38, s98, v142
	v_lshl_add_u64 v[84:85], v[38:39], 1, s[46:47]
	global_load_dwordx4 v[80:83], v[84:85], off nt
	s_nop 0
	global_load_dwordx4 v[84:87], v[84:85], off offset:1024 nt
	v_lshl_add_u64 v[36:37], v[38:39], 1, s[20:21]
	global_load_dwordx4 v[116:119], v[36:37], off nt
	global_load_dwordx4 v[120:123], v[36:37], off offset:1024 nt
.Lrp_pre_done:
	s_waitcnt vmcnt(0)
	s_branch .LBB0_250
.LBB0_249:
	s_add_i32 s68, s66, s30
	s_cmp_gt_i32 s68, 0xffff
	s_cbranch_scc1 .LBB0_309

; __device__ __forceinline__ void row_load(const RowArgs& R, int m, int lane, RowRaw& q) {
;     const size_t off = (size_t)m * DM + 8 * lane;
;     if (R.hin32) {
; #pragma unroll
;         for (int j = 0; j < 2; ++j) { q.v32[j][0] = __builtin_nontemporal_load((const f32x4*)(R.hin32 + off + 512 * j)); q.v32[j][1] = __builtin_nontemporal_load((const f32x4*)(R.hin32 + off + 512 * j + 4)); }
;     } else {
; #pragma unroll
;         for (int j = 0; j < 2; ++j) q.v16[j] = __builtin_nontemporal_load((const u32x4*)(R.hin16 + off + 512 * j));
;     }
;     if (R.F) {
; #pragma unroll
;         for (int j = 0; j < 2; ++j) q.f[j] = __builtin_nontemporal_load((const u32x4*)(R.F + off + 512 * j));
;     }
;     if (R.F2) {
; #pragma unroll
;         for (int j = 0; j < 2; ++j) q.e[j] = __builtin_nontemporal_load((const u32x4*)(R.F2 + off + 512 * j));
;     }
;     if (R.p) q.p = __builtin_nontemporal_load((const f32x4*)(R.p + (size_t)m * PLE + 4 * lane));
.LBB0_253:
	v_mov_b64_e32 v[134:135], v[114:115]
	v_mov_b64_e32 v[138:139], v[110:111]
	v_mov_b64_e32 v[126:127], v[106:107]
	v_mov_b64_e32 v[130:131], v[102:103]
	v_mov_b64_e32 v[132:133], v[112:113]
	v_mov_b64_e32 v[136:137], v[108:109]
	v_mov_b64_e32 v[124:125], v[104:105]
	v_mov_b64_e32 v[128:129], v[100:101]
.LBB0_254:
	s_and_b64 vcc, exec, s[12:13]
	s_cbranch_vccnz .Lrp_skipF1
	v_lshl_add_u64 v[100:101], v[148:149], 1, s[20:21]
	global_load_dwordx4 v[116:119], v[100:101], off nt
	global_load_dwordx4 v[120:123], v[100:101], off offset:1024 nt
.Lrp_skipF1:
	s_andn2_b64 vcc, exec, s[36:37]
	s_cbranch_vccnz .LBB0_256
	v_lshl_add_u64 v[92:93], v[148:149], 1, s[96:97]
	global_load_dwordx4 v[88:91], v[92:93], off nt
	s_nop 0
	global_load_dwordx4 v[92:95], v[92:93], off offset:1024 nt

; #define UNPK_BF(dst, SRC_) do { const u32x4 t_ = (SRC_); dst[0] = bflo(t_.x); dst[1] = bfhi(t_.x); dst[2] = bflo(t_.y); dst[3] = bfhi(t_.y); dst[4] = bflo(t_.z); dst[5] = bfhi(t_.z); dst[6] = bflo(t_.w); dst[7] = bfhi(t_.w); } while (0)
; __device__ __forceinline__ void row_load(const RowArgs& R, int m, int lane, RowRaw& q) {
;     const size_t off = (size_t)m * DM + 8 * lane;
;     if (R.hin32) {
; #pragma unroll
;         for (int j = 0; j < 2; ++j) { q.v32[j][0] = __builtin_nontemporal_load((const f32x4*)(R.hin32 + off + 512 * j)); q.v32[j][1] = __builtin_nontemporal_load((const f32x4*)(R.hin32 + off + 512 * j + 4)); }
;     } else {
; #pragma unroll
;         for (int j = 0; j < 2; ++j) q.v16[j] = __builtin_nontemporal_load((const u32x4*)(R.hin16 + off + 512 * j));
;     }
;     if (R.F) {
; #pragma unroll
;         for (int j = 0; j < 2; ++j) q.f[j] = __builtin_nontemporal_load((const u32x4*)(R.F + off + 512 * j));
;     }
; __device__ __forceinline__ void row_process(const RowArgs& R, int m, int lane, const RowRaw& q, const float (&gp)[2][8], const float (&gn)[2][8], const f32x4 bf, const LAS f32x4* afl) {
;     ...
;     if (R.F) {
;         float f[2][8];
; #pragma unroll
;         for (int j = 0; j < 2; ++j) UNPK_BF(f[j], q.f[j]);
;         if (R.F2) {
;             float e[2][8]; float ss = 0.f;
; #pragma unroll
;             for (int j = 0; j < 2; ++j) { UNPK_BF(e[j], q.e[j]);
; #pragma unroll
;                 for (int c = 0; c < 8; ++c) ss += e[j][c] * e[j][c]; }
;             const float r = 1.0f / sqrtf(wave_sum(ss) * (1.0f / DM) + EPS);
; #pragma unroll
;             for (int j = 0; j < 2; ++j)
; #pragma unroll
;                 for (int c = 0; c < 8; ++c) v[j][c] += (1.0f / (1.0f + expf(-f[j][c]))) * (e[j][c] * r * gp[j][c]);
.LBB0_288:
	v_and_b32_e32 v0, 0xffff0000, v116
	v_lshlrev_b32_e32 v149, 16, v117
	v_lshlrev_b32_e32 v148, 16, v116
	v_and_b32_e32 v151, 0xffff0000, v118
	v_and_b32_e32 v150, 0xffff0000, v117
	v_lshlrev_b32_e32 v153, 16, v119
	v_lshlrev_b32_e32 v152, 16, v118
	v_lshlrev_b32_e32 v156, 16, v120
	v_and_b32_e32 v157, 0xffff0000, v120
	v_lshlrev_b32_e32 v158, 16, v121
	v_and_b32_e32 v159, 0xffff0000, v121
	v_lshlrev_b32_e32 v160, 16, v122
	v_and_b32_e32 v161, 0xffff0000, v122
	v_and_b32_e32 v163, 0xffff0000, v119
	v_lshlrev_b32_e32 v162, 16, v123
	v_and_b32_e32 v154, 0xffff0000, v123
	s_and_b64 vcc, exec, s[12:13]
	s_cbranch_vccz .Lrp_early1_done
	s_add_i32 s98, s89, s66
	s_cmp_gt_i32 s98, 0xffff
	s_cbranch_scc1 .Lrp_early1_done
	s_ashr_i32 s99, s98, 31
	s_lshl_b64 s[98:99], s[98:99], 10
	v_mov_b32_e32 v39, s99
	v_or_b32_e32 v38, s98, v142
	v_lshl_add_u64 v[84:85], v[38:39], 1, s[46:47]
	global_load_dwordx4 v[80:83], v[84:85], off nt
	s_nop 0
	global_load_dwordx4 v[84:87], v[84:85], off offset:1024 nt
	v_lshl_add_u64 v[36:37], v[38:39], 1, s[20:21]
	global_load_dwordx4 v[116:119], v[36:37], off nt
	global_load_dwordx4 v[120:123], v[36:37], off offset:1024 nt
.Lrp_early1_done:
	s_and_b64 vcc, exec, s[36:37]
	s_cbranch_vccz .LBB0_307
	v_mul_f32_e32 v155, 0xbfb8aa3b, v148
	v_rndne_f32_e32 v165, v155
	v_sub_f32_e32 v166, v155, v165
	v_fma_f32 v155, v148, s22, -v155
	v_fmac_f32_e32 v155, 0xb2a5705f, v148
	v_add_f32_e32 v155, v166, v155
	v_exp_f32_e32 v155, v155
	v_cvt_i32_f32_e32 v165, v165
	v_cmp_nlt_f32_e32 vcc, s55, v148
	s_mov_b32 s4, 0xc2b17218
	v_lshlrev_b32_e32 v207, 16, v89
	v_ldexp_f32 v155, v155, v165
	v_cndmask_b32_e32 v155, 0, v155, vcc
	v_cmp_ngt_f32_e32 vcc, s4, v148
	v_lshlrev_b32_e32 v206, 16, v88
	v_and_b32_e32 v143, 0xffff0000, v88
	v_cndmask_b32_e32 v166, v235, v155, vcc
	v_mul_f32_e32 v155, 0xbfb8aa3b, v0
	v_rndne_f32_e32 v165, v155
	v_sub_f32_e32 v167, v155, v165
	v_fma_f32 v155, v0, s22, -v155
	v_fmac_f32_e32 v155, 0xb2a5705f, v0
	v_add_f32_e32 v155, v167, v155
	v_exp_f32_e32 v155, v155
	v_cvt_i32_f32_e32 v165, v165
	v_cmp_nlt_f32_e32 vcc, s55, v0
	v_and_b32_e32 v164, 0xffff0000, v95
	v_pk_mul_f32 v[208:209], v[206:207], v[206:207]
	v_ldexp_f32 v155, v155, v165
	v_mul_f32_e32 v165, 0xbfb8aa3b, v149
	v_rndne_f32_e32 v167, v165
	v_sub_f32_e32 v168, v165, v167
	v_fma_f32 v165, v149, s22, -v165
	v_fmac_f32_e32 v165, 0xb2a5705f, v149
	v_add_f32_e32 v165, v168, v165
	v_exp_f32_e32 v165, v165
	v_cvt_i32_f32_e32 v167, v167
	v_cndmask_b32_e32 v155, 0, v155, vcc
	v_cmp_ngt_f32_e32 vcc, s4, v0
	v_lshlrev_b32_e32 v203, 16, v91
	v_ldexp_f32 v165, v165, v167
	v_cndmask_b32_e32 v155, v235, v155, vcc
	v_cmp_nlt_f32_e32 vcc, s55, v149
	v_lshlrev_b32_e32 v202, 16, v90
	v_pk_mul_f32 v[204:205], v[202:203], v[202:203]
	v_cndmask_b32_e32 v165, 0, v165, vcc
	v_cmp_ngt_f32_e32 vcc, s4, v149
	v_lshlrev_b32_e32 v176, 16, v93
	v_and_b32_e32 v177, 0xffff0000, v93
	v_cndmask_b32_e32 v167, v235, v165, vcc
	v_pk_add_f32 v[166:167], v[166:167], 1.0 op_sel_hi:[1,0]
	v_pk_mul_f32 v[186:187], v[176:177], v[176:177]
	v_div_scale_f32 v165, s[12:13], v167, v167, 1.0
	v_rcp_f32_e32 v168, v165
	v_add_f32_e32 v155, 1.0, v155
	v_fma_f32 v169, -v165, v168, 1.0
	v_fmac_f32_e32 v168, v169, v168
	v_div_scale_f32 v169, vcc, 1.0, v167, 1.0
	v_mul_f32_e32 v170, v169, v168
	v_fma_f32 v171, -v165, v170, v169
	v_fmac_f32_e32 v170, v171, v168
	v_fma_f32 v165, -v165, v170, v169
	v_div_fmas_f32 v165, v165, v168, v170
	v_div_fixup_f32 v167, v165, v167, 1.0
	v_div_scale_f32 v165, s[12:13], v166, v166, 1.0
	v_rcp_f32_e32 v168, v165
	s_nop 0
	v_fma_f32 v169, -v165, v168, 1.0
	v_fmac_f32_e32 v168, v169, v168
	v_div_scale_f32 v169, vcc, 1.0, v166, 1.0
	v_mul_f32_e32 v170, v169, v168
	v_fma_f32 v171, -v165, v170, v169
	v_fmac_f32_e32 v170, v171, v168
	v_fma_f32 v165, -v165, v170, v169
	v_div_fmas_f32 v165, v165, v168, v170
	v_div_fixup_f32 v166, v165, v166, 1.0
	v_mul_f32_e32 v165, 0xbfb8aa3b, v150
	v_rndne_f32_e32 v168, v165
	v_sub_f32_e32 v169, v165, v168
	v_fma_f32 v165, v150, s22, -v165
	v_fmac_f32_e32 v165, 0xb2a5705f, v150
	v_add_f32_e32 v165, v169, v165
	v_exp_f32_e32 v165, v165
	v_cvt_i32_f32_e32 v168, v168
	v_cmp_nlt_f32_e32 vcc, s55, v150
	v_ldexp_f32 v165, v165, v168
	s_nop 0
	v_cndmask_b32_e32 v165, 0, v165, vcc
	v_cmp_ngt_f32_e32 vcc, s4, v150
	s_nop 1
	v_cndmask_b32_e32 v172, v235, v165, vcc
	v_mul_f32_e32 v165, 0xbfb8aa3b, v152
	v_rndne_f32_e32 v168, v165
	v_sub_f32_e32 v169, v165, v168
	v_fma_f32 v165, v152, s22, -v165
	v_fmac_f32_e32 v165, 0xb2a5705f, v152
	v_add_f32_e32 v165, v169, v165
	v_exp_f32_e32 v165, v165
	v_cvt_i32_f32_e32 v168, v168
	v_cmp_nlt_f32_e32 vcc, s55, v152
	v_ldexp_f32 v165, v165, v168
	s_nop 0
	v_cndmask_b32_e32 v165, 0, v165, vcc
	v_cmp_ngt_f32_e32 vcc, s4, v152
	s_nop 1
	v_cndmask_b32_e32 v168, v235, v165, vcc
	v_mul_f32_e32 v165, 0xbfb8aa3b, v151
	v_rndne_f32_e32 v169, v165
	v_sub_f32_e32 v170, v165, v169
	v_fma_f32 v165, v151, s22, -v165
	v_fmac_f32_e32 v165, 0xb2a5705f, v151
	v_add_f32_e32 v165, v170, v165
	v_exp_f32_e32 v165, v165
	v_cvt_i32_f32_e32 v169, v169
	v_cmp_nlt_f32_e32 vcc, s55, v151
	v_ldexp_f32 v165, v165, v169
	s_nop 0
	v_cndmask_b32_e32 v165, 0, v165, vcc
	v_cmp_ngt_f32_e32 vcc, s4, v151
	s_nop 1
	v_cndmask_b32_e32 v173, v235, v165, vcc
	v_mul_f32_e32 v165, 0xbfb8aa3b, v153
	v_rndne_f32_e32 v169, v165
	v_sub_f32_e32 v170, v165, v169
	v_fma_f32 v165, v153, s22, -v165
	v_fmac_f32_e32 v165, 0xb2a5705f, v153
	v_add_f32_e32 v165, v170, v165
	v_exp_f32_e32 v165, v165
	v_cvt_i32_f32_e32 v169, v169
	v_cmp_nlt_f32_e32 vcc, s55, v153
	v_pk_add_f32 v[172:173], v[172:173], 1.0 op_sel_hi:[1,0]
	v_ldexp_f32 v165, v165, v169
; #define UNPK_BF(dst, SRC_) do { const u32x4 t_ = (SRC_); dst[0] = bflo(t_.x); dst[1] = bfhi(t_.x); dst[2] = bflo(t_.y); dst[3] = bfhi(t_.y); dst[4] = bflo(t_.z); dst[5] = bfhi(t_.z); dst[6] = bflo(t_.w); dst[7] = bfhi(t_.w); } while (0)
; __device__ __forceinline__ void row_process(const RowArgs& R, int m, int lane, const RowRaw& q, const float (&gp)[2][8], const float (&gn)[2][8], const f32x4 bf, const LAS f32x4* afl) {
;     ...
;     if (R.F) {
;         float f[2][8];
; #pragma unroll
;         for (int j = 0; j < 2; ++j) UNPK_BF(f[j], q.f[j]);
;         if (R.F2) {
;             float e[2][8]; float ss = 0.f;
; #pragma unroll
;             for (int j = 0; j < 2; ++j) { UNPK_BF(e[j], q.e[j]);
; #pragma unroll
;                 for (int c = 0; c < 8; ++c) ss += e[j][c] * e[j][c]; }
;             const float r = 1.0f / sqrtf(wave_sum(ss) * (1.0f / DM) + EPS);
; #pragma unroll
;             for (int j = 0; j < 2; ++j)
; #pragma unroll
;                 for (int c = 0; c < 8; ++c) v[j][c] += (1.0f / (1.0f + expf(-f[j][c]))) * (e[j][c] * r * gp[j][c]);
	v_cndmask_b32_e32 v165, 0, v165, vcc
	v_cmp_ngt_f32_e32 vcc, s4, v153
	s_nop 1
	v_cndmask_b32_e32 v169, v235, v165, vcc
	v_pk_add_f32 v[168:169], v[168:169], 1.0 op_sel_hi:[1,0]
	s_nop 0
	v_div_scale_f32 v165, s[12:13], v169, v169, 1.0
	v_rcp_f32_e32 v170, v165
	s_nop 0
	v_fma_f32 v171, -v165, v170, 1.0
	v_fmac_f32_e32 v170, v171, v170
	v_div_scale_f32 v171, vcc, 1.0, v169, 1.0
	v_mul_f32_e32 v174, v171, v170
	v_fma_f32 v175, -v165, v174, v171
	v_fmac_f32_e32 v174, v175, v170
	v_fma_f32 v165, -v165, v174, v171
	v_div_fmas_f32 v165, v165, v170, v174
	v_div_fixup_f32 v169, v165, v169, 1.0
	v_div_scale_f32 v165, s[12:13], v168, v168, 1.0
	v_rcp_f32_e32 v170, v165
	s_nop 0
	v_fma_f32 v171, -v165, v170, 1.0
	v_fmac_f32_e32 v170, v171, v170
	v_div_scale_f32 v171, vcc, 1.0, v168, 1.0
	v_mul_f32_e32 v174, v171, v170
	v_fma_f32 v175, -v165, v174, v171
	v_fmac_f32_e32 v174, v175, v170
	v_fma_f32 v165, -v165, v174, v171
	v_div_fmas_f32 v165, v165, v170, v174
	v_div_fixup_f32 v168, v165, v168, 1.0
	v_mul_f32_e32 v165, 0xbfb8aa3b, v163
	v_rndne_f32_e32 v170, v165
	v_sub_f32_e32 v171, v165, v170
	v_fma_f32 v165, v163, s22, -v165
	v_fmac_f32_e32 v165, 0xb2a5705f, v163
	v_add_f32_e32 v165, v171, v165
	v_exp_f32_e32 v165, v165
	v_cvt_i32_f32_e32 v170, v170
	v_cmp_nlt_f32_e32 vcc, s55, v163
	v_and_b32_e32 v175, 0xffff0000, v94
	v_ldexp_f32 v165, v165, v170
	v_cndmask_b32_e32 v165, 0, v165, vcc
	v_cmp_ngt_f32_e32 vcc, s4, v163
	s_nop 1
	v_cndmask_b32_e32 v171, v235, v165, vcc
	v_mul_f32_e32 v165, 0xbfb8aa3b, v156
	v_rndne_f32_e32 v170, v165
	v_sub_f32_e32 v174, v165, v170
	v_fma_f32 v165, v156, s22, -v165
	v_fmac_f32_e32 v165, 0xb2a5705f, v156
	v_add_f32_e32 v165, v174, v165
	v_exp_f32_e32 v165, v165
	v_cvt_i32_f32_e32 v170, v170
	v_cmp_nlt_f32_e32 vcc, s55, v156
	v_ldexp_f32 v165, v165, v170
	s_nop 0
	v_cndmask_b32_e32 v165, 0, v165, vcc
	v_cmp_ngt_f32_e32 vcc, s4, v156
	s_nop 1
	v_cndmask_b32_e32 v182, v235, v165, vcc
	v_mul_f32_e32 v165, 0xbfb8aa3b, v157
	v_rndne_f32_e32 v170, v165
	v_sub_f32_e32 v174, v165, v170
	v_fma_f32 v165, v157, s22, -v165
	v_fmac_f32_e32 v165, 0xb2a5705f, v157
	v_add_f32_e32 v165, v174, v165
	v_exp_f32_e32 v165, v165
	v_cvt_i32_f32_e32 v170, v170
	v_cmp_nlt_f32_e32 vcc, s55, v157
	v_ldexp_f32 v165, v165, v170
	s_nop 0
	v_cndmask_b32_e32 v165, 0, v165, vcc
	v_cmp_ngt_f32_e32 vcc, s4, v157
	s_nop 1
	v_cndmask_b32_e32 v183, v235, v165, vcc
	v_mul_f32_e32 v165, 0xbfb8aa3b, v158
	v_rndne_f32_e32 v170, v165
	v_sub_f32_e32 v174, v165, v170
	v_fma_f32 v165, v158, s22, -v165
	v_fmac_f32_e32 v165, 0xb2a5705f, v158
	v_add_f32_e32 v165, v174, v165
	v_exp_f32_e32 v165, v165
	v_cvt_i32_f32_e32 v170, v170
	v_cmp_nlt_f32_e32 vcc, s55, v158
	v_pk_add_f32 v[182:183], v[182:183], 1.0 op_sel_hi:[1,0]
	v_ldexp_f32 v165, v165, v170
	v_cndmask_b32_e32 v165, 0, v165, vcc
	v_cmp_ngt_f32_e32 vcc, s4, v158
	s_nop 1
	v_cndmask_b32_e32 v178, v235, v165, vcc
	v_mul_f32_e32 v165, 0xbfb8aa3b, v159
	v_rndne_f32_e32 v170, v165
	v_sub_f32_e32 v174, v165, v170
	v_fma_f32 v165, v159, s22, -v165
	v_fmac_f32_e32 v165, 0xb2a5705f, v159
	v_add_f32_e32 v165, v174, v165
	v_exp_f32_e32 v165, v165
	v_cvt_i32_f32_e32 v170, v170
	v_cmp_nlt_f32_e32 vcc, s55, v159
	v_ldexp_f32 v165, v165, v170
	s_nop 0
	v_cndmask_b32_e32 v165, 0, v165, vcc
	v_cmp_ngt_f32_e32 vcc, s4, v159
	s_nop 1
	v_cndmask_b32_e32 v179, v235, v165, vcc
	v_mul_f32_e32 v165, 0xbfb8aa3b, v160
	v_rndne_f32_e32 v170, v165
	v_sub_f32_e32 v174, v165, v170
	v_fma_f32 v165, v160, s22, -v165
	v_fmac_f32_e32 v165, 0xb2a5705f, v160
	v_add_f32_e32 v165, v174, v165
	v_exp_f32_e32 v165, v165
	v_cvt_i32_f32_e32 v170, v170
	v_cmp_nlt_f32_e32 vcc, s55, v160
	v_pk_add_f32 v[178:179], v[178:179], 1.0 op_sel_hi:[1,0]
	v_ldexp_f32 v165, v165, v170
	v_cndmask_b32_e32 v165, 0, v165, vcc
	v_cmp_ngt_f32_e32 vcc, s4, v160
	s_nop 1
	v_cndmask_b32_e32 v194, v235, v165, vcc
	v_mul_f32_e32 v165, 0xbfb8aa3b, v161
	v_rndne_f32_e32 v170, v165
	v_sub_f32_e32 v174, v165, v170
	v_fma_f32 v165, v161, s22, -v165
	v_fmac_f32_e32 v165, 0xb2a5705f, v161
	v_add_f32_e32 v165, v174, v165
	v_exp_f32_e32 v165, v165
	v_cvt_i32_f32_e32 v170, v170
	v_cmp_nlt_f32_e32 vcc, s55, v161
	v_lshlrev_b32_e32 v174, 16, v94
	v_pk_mul_f32 v[184:185], v[174:175], v[174:175]
	v_ldexp_f32 v165, v165, v170
	v_cndmask_b32_e32 v165, 0, v165, vcc
	v_cmp_ngt_f32_e32 vcc, s4, v161
	s_nop 1
	v_cndmask_b32_e32 v195, v235, v165, vcc
	v_div_scale_f32 v165, s[12:13], v179, v179, 1.0
	v_rcp_f32_e32 v170, v165
	s_nop 0
	v_fma_f32 v180, -v165, v170, 1.0
	v_fmac_f32_e32 v170, v180, v170
	v_div_scale_f32 v180, vcc, 1.0, v179, 1.0
	v_mul_f32_e32 v181, v180, v170
	v_fma_f32 v188, -v165, v181, v180
	v_fmac_f32_e32 v181, v188, v170
	v_fma_f32 v165, -v165, v181, v180
	v_div_fmas_f32 v165, v165, v170, v181
	v_div_fixup_f32 v179, v165, v179, 1.0
	v_div_scale_f32 v165, s[12:13], v178, v178, 1.0
	v_rcp_f32_e32 v170, v165
	s_nop 0
	v_fma_f32 v180, -v165, v170, 1.0
	v_fmac_f32_e32 v170, v180, v170
	v_div_scale_f32 v180, vcc, 1.0, v178, 1.0
	v_mul_f32_e32 v181, v180, v170
	v_fma_f32 v188, -v165, v181, v180
	v_fmac_f32_e32 v181, v188, v170
	v_fma_f32 v165, -v165, v181, v180
	v_div_fmas_f32 v165, v165, v170, v181
	v_div_fixup_f32 v178, v165, v178, 1.0
	v_div_scale_f32 v165, s[12:13], v183, v183, 1.0
	v_rcp_f32_e32 v170, v165
	v_lshlrev_b32_e32 v180, 16, v92
	v_and_b32_e32 v181, 0xffff0000, v92
	v_pk_mul_f32 v[192:193], v[180:181], v[180:181]
	v_fma_f32 v188, -v165, v170, 1.0
	v_fmac_f32_e32 v170, v188, v170
	v_div_scale_f32 v188, vcc, 1.0, v183, 1.0
	v_mul_f32_e32 v189, v188, v170
	v_fma_f32 v190, -v165, v189, v188
	v_fmac_f32_e32 v189, v190, v170
	v_fma_f32 v165, -v165, v189, v188
; template <int CTRL> __device__ __forceinline__ float dpp_f(float v) { return __builtin_bit_cast(float, __builtin_amdgcn_update_dpp(0, __builtin_bit_cast(int, v), CTRL, 0xf, 0xf, false)); }
; #define UNPK_BF(dst, SRC_) do { const u32x4 t_ = (SRC_); dst[0] = bflo(t_.x); dst[1] = bfhi(t_.x); dst[2] = bflo(t_.y); dst[3] = bfhi(t_.y); dst[4] = bflo(t_.z); dst[5] = bfhi(t_.z); dst[6] = bflo(t_.w); dst[7] = bfhi(t_.w); } while (0)
; __device__ __forceinline__ float wave_sum(float v) {
;     v += dpp_f<0xB1>(v);
;     v += dpp_f<0x4E>(v);
;     v += dpp_f<0x141>(v);
;     v += dpp_f<0x140>(v);
;     const int b = __builtin_bit_cast(int, v);
;     const float r0 = __builtin_bit_cast(float, __builtin_amdgcn_readlane(b, 0)), r1 = __builtin_bit_cast(float, __builtin_amdgcn_readlane(b, 16));
;     const float r2 = __builtin_bit_cast(float, __builtin_amdgcn_readlane(b, 32)), r3 = __builtin_bit_cast(float, __builtin_amdgcn_readlane(b, 48));
;     return (r0 + r1) + (r2 + r3);
; __device__ __forceinline__ void row_process(const RowArgs& R, int m, int lane, const RowRaw& q, const float (&gp)[2][8], const float (&gn)[2][8], const f32x4 bf, const LAS f32x4* afl) {
;     ...
;             for (int j = 0; j < 2; ++j) { UNPK_BF(e[j], q.e[j]);
; #pragma unroll
;                 for (int c = 0; c < 8; ++c) ss += e[j][c] * e[j][c]; }
;             const float r = 1.0f / sqrtf(wave_sum(ss) * (1.0f / DM) + EPS);
	v_div_fmas_f32 v165, v165, v170, v189
	v_div_fixup_f32 v183, v165, v183, 1.0
	v_div_scale_f32 v165, s[12:13], v182, v182, 1.0
	v_rcp_f32_e32 v170, v165
	s_nop 0
	v_fma_f32 v188, -v165, v170, 1.0
	v_fmac_f32_e32 v170, v188, v170
	v_div_scale_f32 v188, vcc, 1.0, v182, 1.0
	v_mul_f32_e32 v189, v188, v170
	v_fma_f32 v190, -v165, v189, v188
	v_fmac_f32_e32 v189, v190, v170
	v_fma_f32 v165, -v165, v189, v188
	v_div_fmas_f32 v165, v165, v170, v189
	v_div_fixup_f32 v182, v165, v182, 1.0
	v_div_scale_f32 v165, s[12:13], v173, v173, 1.0
	v_rcp_f32_e32 v170, v165
	v_and_b32_e32 v189, 0xffff0000, v90
	v_and_b32_e32 v188, 0xffff0000, v89
	v_pk_mul_f32 v[198:199], v[188:189], v[188:189]
	v_fma_f32 v190, -v165, v170, 1.0
	v_fmac_f32_e32 v170, v190, v170
	v_div_scale_f32 v190, vcc, 1.0, v173, 1.0
	v_mul_f32_e32 v191, v190, v170
	v_fma_f32 v197, -v165, v191, v190
	v_fmac_f32_e32 v191, v197, v170
	v_fma_f32 v165, -v165, v191, v190
	v_div_fmas_f32 v165, v165, v170, v191
	v_div_fixup_f32 v191, v165, v173, 1.0
	v_div_scale_f32 v165, s[12:13], v172, v172, 1.0
	v_rcp_f32_e32 v170, v165
	s_nop 0
	v_fma_f32 v173, -v165, v170, 1.0
	v_fmac_f32_e32 v170, v173, v170
	v_div_scale_f32 v173, vcc, 1.0, v172, 1.0
	v_mul_f32_e32 v190, v173, v170
	v_fma_f32 v197, -v165, v190, v173
	v_fmac_f32_e32 v190, v197, v170
	v_fma_f32 v165, -v165, v190, v173
	v_div_fmas_f32 v165, v165, v170, v190
	v_div_fixup_f32 v190, v165, v172, 1.0
	v_pk_add_f32 v[172:173], v[194:195], 1.0 op_sel_hi:[1,0]
	s_nop 0
	v_div_scale_f32 v165, s[12:13], v173, v173, 1.0
	v_rcp_f32_e32 v170, v165
	s_nop 0
	v_fma_f32 v194, -v165, v170, 1.0
	v_fmac_f32_e32 v170, v194, v170
	v_div_scale_f32 v194, vcc, 1.0, v173, 1.0
	v_mul_f32_e32 v195, v194, v170
	v_fma_f32 v197, -v165, v195, v194
	v_fmac_f32_e32 v195, v197, v170
	v_fma_f32 v165, -v165, v195, v194
	v_div_fmas_f32 v165, v165, v170, v195
	v_div_fixup_f32 v173, v165, v173, 1.0
	v_div_scale_f32 v165, s[12:13], v172, v172, 1.0
	v_rcp_f32_e32 v170, v165
	s_nop 0
	v_fma_f32 v194, -v165, v170, 1.0
	v_fmac_f32_e32 v170, v194, v170
	v_div_scale_f32 v194, vcc, 1.0, v172, 1.0
	v_mul_f32_e32 v195, v194, v170
	v_fma_f32 v197, -v165, v195, v194
	v_fmac_f32_e32 v195, v197, v170
	v_fma_f32 v165, -v165, v195, v194
	v_div_fmas_f32 v165, v165, v170, v195
	v_div_fixup_f32 v172, v165, v172, 1.0
	v_mul_f32_e32 v165, 0xbfb8aa3b, v162
	v_rndne_f32_e32 v170, v165
	v_sub_f32_e32 v194, v165, v170
	v_fma_f32 v165, v162, s22, -v165
	v_fmac_f32_e32 v165, 0xb2a5705f, v162
	v_add_f32_e32 v165, v194, v165
	v_exp_f32_e32 v165, v165
	v_cvt_i32_f32_e32 v170, v170
	v_cmp_nlt_f32_e32 vcc, s55, v162
	v_lshlrev_b32_e32 v194, 16, v95
	v_and_b32_e32 v195, 0xffff0000, v91
	v_ldexp_f32 v165, v165, v170
	v_cndmask_b32_e32 v165, 0, v165, vcc
	v_cmp_ngt_f32_e32 vcc, s4, v162
	s_nop 1
	v_cndmask_b32_e32 v170, v235, v165, vcc
	v_mov_b32_e32 v165, v194
	v_pk_mul_f32 v[200:201], v[164:165], v[164:165]
	v_fma_f32 v165, v143, v143, v208
	v_add_f32_e32 v165, v209, v165
	v_add_f32_e32 v165, v198, v165
	v_add_f32_e32 v165, v204, v165
	v_add_f32_e32 v165, v199, v165
	v_add_f32_e32 v165, v205, v165
	v_fmac_f32_e32 v165, v195, v195
	v_add_f32_e32 v165, v192, v165
	v_add_f32_e32 v165, v193, v165
	v_add_f32_e32 v165, v186, v165
	v_add_f32_e32 v165, v187, v165
	v_add_f32_e32 v165, v184, v165
	v_add_f32_e32 v165, v185, v165
	v_add_f32_e32 v165, v201, v165
	v_add_f32_e32 v165, v200, v165
	v_pk_add_f32 v[170:171], v[170:171], 1.0 op_sel_hi:[1,0]
	v_mov_b32_e32 v193, v164
	v_add_f32_dpp v165, v165, v165 quad_perm:[1,0,3,2] row_mask:0xf bank_mask:0xf bound_ctrl:1
	s_nop 1
	v_add_f32_dpp v165, v165, v165 quad_perm:[2,3,0,1] row_mask:0xf bank_mask:0xf bound_ctrl:1
	s_nop 1
	v_add_f32_dpp v165, v165, v165 row_half_mirror row_mask:0xf bank_mask:0xf bound_ctrl:1
	s_nop 1
	v_add_f32_dpp v165, v165, v165 row_mirror row_mask:0xf bank_mask:0xf bound_ctrl:1
	s_nop 0
	v_readlane_b32 s1, v165, 16
	v_readlane_b32 s3, v165, 48
	v_readlane_b32 s12, v165, 0
	v_readlane_b32 s13, v165, 32
	v_mov_b32_e32 v184, s1
	v_mov_b32_e32 v185, s3
	v_pk_add_f32 v[184:185], s[12:13], v[184:185]
	s_nop 0
	v_add_f32_e32 v165, v184, v185
	v_fmamk_f32 v165, v165, 0x3a800000, v229
	v_cmp_gt_f32_e32 vcc, s59, v165
	v_mul_f32_e32 v184, 0x4f800000, v165
	s_nop 0
	v_cndmask_b32_e32 v165, v165, v184, vcc
; __device__ __forceinline__ void row_process(const RowArgs& R, int m, int lane, const RowRaw& q, const float (&gp)[2][8], const float (&gn)[2][8], const f32x4 bf, const LAS f32x4* afl) {
;     ...
;             const float r = 1.0f / sqrtf(wave_sum(ss) * (1.0f / DM) + EPS);
; #pragma unroll
;             for (int j = 0; j < 2; ++j)
; #pragma unroll
;                 for (int c = 0; c < 8; ++c) v[j][c] += (1.0f / (1.0f + expf(-f[j][c]))) * (e[j][c] * r * gp[j][c]);
	v_sqrt_f32_e32 v184, v165
	s_nop 0
	v_add_u32_e32 v185, -1, v184
	v_fma_f32 v186, -v185, v184, v165
	v_cmp_ge_f32_e64 s[12:13], 0, v186
	v_add_u32_e32 v186, 1, v184
	s_nop 0
	v_cndmask_b32_e64 v185, v184, v185, s[12:13]
	v_fma_f32 v184, -v186, v184, v165
	v_cmp_lt_f32_e64 s[12:13], 0, v184
	s_nop 1
	v_cndmask_b32_e64 v184, v185, v186, s[12:13]
	v_mul_f32_e32 v185, 0x37800000, v184
	v_cndmask_b32_e32 v184, v184, v185, vcc
	v_cmp_class_f32_e32 vcc, v165, v230
	s_nop 1
	v_cndmask_b32_e32 v165, v184, v165, vcc
	v_div_scale_f32 v184, s[12:13], v165, v165, 1.0
	v_rcp_f32_e32 v185, v184
	s_nop 0
	v_fma_f32 v186, -v184, v185, 1.0
	v_fmac_f32_e32 v185, v186, v185
	v_div_scale_f32 v186, vcc, 1.0, v165, 1.0
	v_mul_f32_e32 v187, v186, v185
	v_fma_f32 v192, -v184, v187, v186
	v_fmac_f32_e32 v187, v192, v185
	v_fma_f32 v184, -v184, v187, v186
	v_div_fmas_f32 v184, v184, v185, v187
	v_div_fixup_f32 v187, v184, v165, 1.0
	v_div_scale_f32 v165, s[12:13], v155, v155, 1.0
	v_rcp_f32_e32 v184, v165
	v_mul_f32_e32 v143, v187, v143
	v_mov_b32_e32 v198, v187
	v_pk_mul_f32 v[176:177], v[198:199], v[176:177] op_sel_hi:[0,1]
	v_fma_f32 v185, -v165, v184, 1.0
	v_fmac_f32_e32 v184, v185, v184
	v_div_scale_f32 v185, vcc, 1.0, v155, 1.0
	v_mul_f32_e32 v186, v185, v184
	v_fma_f32 v192, -v165, v186, v185
	v_fmac_f32_e32 v186, v192, v184
	v_fma_f32 v165, -v165, v186, v185
	v_div_fmas_f32 v165, v165, v184, v186
	v_mul_f32_e32 v192, v196, v143
	v_div_scale_f32 v143, s[12:13], v171, v171, 1.0
	v_div_fixup_f32 v186, v165, v155, 1.0
	v_rcp_f32_e32 v155, v143
	v_pk_mul_f32 v[184:185], v[198:199], v[206:207] op_sel_hi:[0,1]
	v_pk_mul_f32 v[184:185], v[6:7], v[184:185]
	v_pk_mul_f32 v[176:177], v[22:23], v[176:177]
	v_pk_mul_f32 v[166:167], v[166:167], v[184:185]
	v_pk_mul_f32 v[184:185], v[198:199], v[188:189] op_sel_hi:[0,1]
	v_pk_mul_f32 v[188:189], v[198:199], v[202:203] op_sel_hi:[0,1]
	v_fma_f32 v165, -v143, v155, 1.0
	v_pk_mul_f32 v[188:189], v[12:13], v[188:189]
	v_fmac_f32_e32 v155, v165, v155
	v_div_scale_f32 v165, vcc, 1.0, v171, 1.0
	v_pk_mul_f32 v[168:169], v[168:169], v[188:189]
	v_mul_f32_e32 v188, v165, v155
	v_fma_f32 v189, -v143, v188, v165
	v_fmac_f32_e32 v188, v189, v155
	v_fma_f32 v143, -v143, v188, v165
	v_div_fmas_f32 v143, v143, v155, v188
	v_div_fixup_f32 v189, v143, v171, 1.0
	v_div_scale_f32 v143, s[12:13], v170, v170, 1.0
	v_rcp_f32_e32 v155, v143
	v_pk_mul_f32 v[176:177], v[178:179], v[176:177]
	v_pk_mul_f32 v[184:185], v[140:141], v[184:185]
	v_pk_mul_f32 v[174:175], v[198:199], v[174:175] op_sel_hi:[0,1]
	v_fma_f32 v165, -v143, v155, 1.0
	v_fmac_f32_e32 v155, v165, v155
	v_div_scale_f32 v165, vcc, 1.0, v170, 1.0
	v_mul_f32_e32 v171, v165, v155
	v_fma_f32 v188, -v143, v171, v165
	v_fmac_f32_e32 v171, v188, v155
	v_fma_f32 v143, -v143, v171, v165
	v_div_fmas_f32 v143, v143, v155, v171
	v_div_fixup_f32 v188, v143, v170, 1.0
	v_mul_f32_e32 v143, 0xbfb8aa3b, v154
	v_rndne_f32_e32 v155, v143
	v_sub_f32_e32 v165, v143, v155
	v_fma_f32 v143, v154, s22, -v143
	v_fmac_f32_e32 v143, 0xb2a5705f, v154
	v_add_f32_e32 v143, v165, v143
	v_exp_f32_e32 v143, v143
	v_cvt_i32_f32_e32 v155, v155
	v_cmp_nlt_f32_e32 vcc, s55, v154
	v_pk_mul_f32 v[170:171], v[198:199], v[194:195] op_sel_hi:[0,1]
	v_pk_mul_f32 v[184:185], v[190:191], v[184:185]
	v_ldexp_f32 v143, v143, v155
	v_cndmask_b32_e32 v143, 0, v143, vcc
	v_cmp_ngt_f32_e32 vcc, s4, v154
	v_pk_mul_f32 v[190:191], v[14:15], v[170:171]
	v_pk_mul_f32 v[170:171], v[198:199], v[180:181] op_sel_hi:[0,1]
	v_cndmask_b32_e32 v143, v235, v143, vcc
	v_add_f32_e32 v143, 1.0, v143
	v_div_scale_f32 v155, s[12:13], v143, v143, 1.0
	v_rcp_f32_e32 v165, v155
	v_pk_mul_f32 v[170:171], v[20:21], v[170:171]
	v_pk_mul_f32 v[174:175], v[28:29], v[174:175]
	v_pk_mul_f32 v[170:171], v[182:183], v[170:171]
	v_fma_f32 v178, -v155, v165, 1.0
	v_fmac_f32_e32 v165, v178, v165
	v_div_scale_f32 v178, vcc, 1.0, v143, 1.0
	v_mul_f32_e32 v179, v178, v165
	v_fma_f32 v180, -v155, v179, v178
	v_fmac_f32_e32 v179, v180, v165
	v_fma_f32 v155, -v155, v179, v178
	v_div_fmas_f32 v155, v155, v165, v179
	v_pk_mul_f32 v[174:175], v[172:173], v[174:175]
	v_pk_mul_f32 v[172:173], v[188:189], v[190:191]
	v_div_fixup_f32 v143, v155, v143, 1.0
	v_pk_mul_f32 v[164:165], v[186:187], v[192:193]
	s_cbranch_execnz .LBB0_291
